# v82 + eighth SSD causal block: last two B-fragment reads issued up front
# baseline (speedup 1.0000x reference)
; #define LAS __attribute__((address_space(3)))
; __device__ __forceinline__ unsigned cvt_pk_bf16(float lo, float hi) { unsigned r; asm volatile("v_cvt_pk_bf16_f32 %0, %1, %2" : "=v"(r) : "v"(lo), "v"(hi)); return r; }
; __device__ __forceinline__ void ssd_phase(const bf16_t* XBC, const float* DT  , const ss_t* SSq, const float* dtb, const bf16_t* Z, const float* a_log, const float* d_skip, bf16_t* YS, LAS unsigned char* lds, int tid, int wid, int lane, int bid, int G) {
;     ...
;                 if (t <= wid) {
;                     f32x4 acc = (f32x4){0.f, 0.f, 0.f, 0.f};
; #pragma unroll
;                     for (int ks = 0; ks < 4; ++ks) { const bf16x8 bfr = *(const LAS bf16x8*)(Bt + (16 * t + fr) * SS_RS + 32 * ks + 8 * fq); acc = __builtin_amdgcn_mfma_f32_16x16x32_bf16(bfr, Cfr[ks], acc, 0, 0, 0); }
;                     const f32x4 cs4 = *(const LAS f32x4*)(csv + 16 * t + 4 * fq); float v[4];
; #pragma unroll
;                     for (int r = 0; r < 4; ++r) { const int sx = 16 * t + 4 * fq + r; v[r] = (sx <= lrow) ? acc[r] * __expf(csl - cs4[r]) : 0.f; }
;                     gp[t][0] = cvt_pk_bf16(v[0], v[1]); gp[t][1] = cvt_pk_bf16(v[2], v[3]);
;                 } else { gp[t][0] = 0u; gp[t][1] = 0u; }
.LBB0_133:
	s_andn2_b64 vcc, exec, s[28:29]
	s_mov_b64 s[30:31], -1
	s_cbranch_vccnz .LBB0_135
	ds_read_b128 v[6:9], v232 offset:34816
	ds_read_b128 v[90:93], v90 offset:448
	ds_read_b128 v[100:103], v232 offset:34880
	ds_read_b128 v[240:243], v232 offset:34944
	ds_read_b128 v[244:247], v232 offset:35008
	s_mov_b64 s[30:31], 0
	s_waitcnt lgkmcnt(4)
	v_mfma_f32_16x16x32_bf16 v[6:9], v[6:9], v[86:89], 0
	s_waitcnt lgkmcnt(3)
	v_sub_f32_e32 v1, v131, v90
	v_mul_f32_e32 v1, 0x3fb8aa3b, v1
	v_exp_f32_e32 v1, v1
	s_waitcnt lgkmcnt(2)
	v_mfma_f32_16x16x32_bf16 v[6:9], v[100:103], v[82:85], v[6:9]
	s_waitcnt lgkmcnt(1)
	v_mfma_f32_16x16x32_bf16 v[6:9], v[240:243], v[78:81], v[6:9]
	s_waitcnt lgkmcnt(0)
	v_mfma_f32_16x16x32_bf16 v[6:9], v[244:247], v[74:77], v[6:9]
	s_nop 1
	s_nop 7
	v_mul_f32_e32 v1, v6, v1
	v_sub_f32_e32 v6, v131, v91
	v_mul_f32_e32 v6, 0x3fb8aa3b, v6
	v_exp_f32_e32 v6, v6
	v_cndmask_b32_e64 v1, v1, 0, s[76:77]
	v_mul_f32_e32 v6, v7, v6
	v_sub_f32_e32 v7, v131, v92
	v_mul_f32_e32 v7, 0x3fb8aa3b, v7
	v_exp_f32_e32 v7, v7
	v_cndmask_b32_e64 v6, v6, 0, s[78:79]
	v_cvt_pk_bf16_f32 v100, v1, v6
	v_mul_f32_e32 v7, v8, v7
	v_sub_f32_e32 v8, v131, v93
	v_mul_f32_e32 v8, 0x3fb8aa3b, v8
	v_exp_f32_e32 v8, v8
	v_cndmask_b32_e64 v7, v7, 0, s[80:81]
	v_mul_f32_e32 v8, v9, v8
	v_cndmask_b32_e64 v8, v8, 0, s[82:83]
	v_cvt_pk_bf16_f32 v101, v7, v8
